# v55 + one static s_setprio 1 for waves 4-7 at each GEMM phase entry (no per-phase flips)
# baseline (speedup 1.0000x reference)
.LBB0_250:
	s_lshr_b32 s0, s75, 1
	s_lshl_b32 s42, s75, 3
	v_writelane_b32 v254, s0, 27
	s_and_b32 s0, s75, 1
	s_cmp_eq_u32 s0, 0
	s_cselect_b64 s[4:5], -1, 0
	v_writelane_b32 v254, s4, 16
	s_cmp_eq_u32 s0, 1
	s_cselect_b64 s[0:1], -1, 0
	v_writelane_b32 v254, s5, 17
	v_writelane_b32 v254, s0, 24
	s_nop 1
	v_writelane_b32 v254, s1, 25
	s_or_b32 s0, s42, 4
	v_readlane_b32 s4, v254, 1
	v_readlane_b32 s5, v254, 2
	s_mov_b64 s[8:9], s[4:5]
	s_cmp_le_i32 s8, s0
	v_readlane_b32 s6, v254, 3
	v_readlane_b32 s7, v254, 4
	s_cselect_b64 s[4:5], -1, 0
	s_cmp_lt_i32 s0, s9
	s_cselect_b64 s[6:7], -1, 0
	s_and_b64 s[4:5], s[4:5], s[6:7]
	s_andn2_b64 vcc, exec, s[4:5]
	s_cbranch_vccnz .LBB0_312
	v_mov_b32_e32 v1, v0
	s_mov_b32 s4, 19
	s_ashr_i32 s5, s4, 31
	s_lshl_b64 s[4:5], s[4:5], 3
	v_readlane_b32 s0, v254, 7
	v_readlane_b32 s1, v254, 8
	s_add_u32 s4, s0, s4
	s_addc_u32 s5, s1, s5
	s_load_dwordx2 s[6:7], s[4:5], 0x0
	v_readlane_b32 s0, v254, 24
	v_readlane_b32 s1, v254, 25
	s_mov_b64 s[4:5], -1
	s_waitcnt lgkmcnt(0)
	s_add_u32 s79, s6, 0x1b000000
	s_addc_u32 s28, s7, 0
	s_add_u32 s52, s6, 0x23000000
	s_addc_u32 s53, s7, 0
	s_and_b64 vcc, exec, s[0:1]
	s_cbranch_vccz .LBB0_275
	v_readlane_b32 s0, v254, 29
	v_readlane_b32 s1, v254, 30
	s_andn2_b64 vcc, exec, s[0:1]
	v_readfirstlane_b32 s38, v1
	s_cbranch_vccnz .LBB0_274
	v_lshlrev_b32_e32 v13, 4, v1
	v_add_u32_e32 v2, 0x2000, v13
	v_ashrrev_i32_e32 v3, 31, v2
	v_lshrrev_b32_e32 v3, 22, v3
	v_add_u32_e32 v3, v2, v3
	v_ashrrev_i32_e32 v10, 10, v3
	v_mul_i32_i24_e32 v4, 0x400, v10
	v_sub_u32_e32 v2, v2, v4
	v_lshrrev_b32_e32 v4, 4, v2
	v_bitop3_b32 v2, v4, v2, 32 bitop3:0x6c
	v_ashrrev_i32_e32 v4, 31, v2
	v_lshrrev_b32_e32 v4, 26, v4
	v_add_u32_e32 v4, v2, v4
	v_ashrrev_i32_e32 v11, 6, v4
	v_and_b32_e32 v4, 0xc0, v4
	v_sub_u32_e32 v2, v2, v4
	v_lshlrev_b32_e32 v3, 5, v10
	v_ashrrev_i16_sdwa v2, v233, sext(v2) dst_sel:DWORD dst_unused:UNUSED_PAD src0_sel:DWORD src1_sel:BYTE_0
	v_and_b32_e32 v3, 32, v3
	v_bfe_i32 v12, v2, 0, 16
	v_add_u32_e32 v2, v3, v12
	v_lshlrev_b32_e32 v3, 3, v10
	v_and_b32_e32 v3, 0xffff0, v3
	v_add_lshl_u32 v3, v11, v3, 12
	v_lshl_add_u32 v130, v2, 1, v3
	v_bfe_i32 v3, v1, 27, 1
	v_lshrrev_b32_e32 v3, 22, v3
	v_add_u32_e32 v3, v13, v3
	v_and_b32_e32 v3, 0xfffffc00, v3
	v_sub_u32_e32 v3, v13, v3
	v_lshrrev_b32_e32 v4, 4, v3
	v_bitop3_b32 v3, v4, v3, 32 bitop3:0x6c
	v_readlane_b32 s1, v254, 27
	v_ashrrev_i32_e32 v4, 31, v3
	s_mul_hi_u32 s0, s1, 0x1800000
	s_mul_i32 s1, s1, 0x1800000
	v_lshrrev_b32_e32 v4, 26, v4
	s_add_u32 s1, s6, s1
	v_ashrrev_i32_e32 v2, 31, v1
	v_add_u32_e32 v4, v3, v4
	s_addc_u32 s0, s7, s0
	v_lshrrev_b32_e32 v2, 26, v2
	v_ashrrev_i32_e32 v15, 6, v4
	v_and_b32_e32 v4, 0xc0, v4
	s_add_u32 s8, s1, 0x6800000
	v_add_u32_e32 v2, v1, v2
	v_sub_u32_e32 v3, v3, v4
	s_addc_u32 s9, s0, 0
	s_ashr_i32 s33, s38, 6
	v_ashrrev_i32_e32 v14, 6, v2
	v_ashrrev_i16_sdwa v3, v233, sext(v3) dst_sel:DWORD dst_unused:UNUSED_PAD src0_sel:DWORD src1_sel:BYTE_0
	s_ashr_i32 s98, s38, 8
	s_cbranch_scc0 .Lsprio_skip_ine
	s_setprio 1
.Lsprio_skip_ine:
	s_ashr_i32 s36, s38, 8
	s_lshl_b32 s20, s33, 10
	v_lshlrev_b32_e32 v2, 5, v14
	v_bfe_i32 v16, v3, 0, 16
	v_lshlrev_b32_e32 v3, 3, v14
	v_readlane_b32 s0, v254, 56
	v_and_b32_e32 v2, 32, v2
	v_and_b32_e32 v3, 0xffff0, v3
	v_readlane_b32 s1, v254, 57
	s_add_u32 s84, s8, s0
	v_add_u32_e32 v2, v2, v16
	v_add_lshl_u32 v3, v15, v3, 12
	s_addc_u32 s85, s9, s1
	s_add_i32 s21, s20, 0
	v_lshl_add_u32 v132, v2, 1, v3
	s_add_i32 m0, s21, 0x10000
	v_readlane_b32 s0, v254, 54
	global_load_lds_dwordx4 v132, s[84:85]
	s_add_i32 m0, s21, 0x12000
	s_add_u32 s4, s84, 0x80000
	global_load_lds_dwordx4 v130, s[84:85]
	s_addc_u32 s5, s85, 0
	s_add_i32 m0, s21, 0x14000
	v_readlane_b32 s1, v254, 55
	global_load_lds_dwordx4 v132, s[4:5]
	s_add_i32 m0, s21, 0x16000
	s_add_u32 s76, s79, s0
	s_addc_u32 s77, s28, s1
	s_add_i32 s26, s21, 0x2000
	global_load_lds_dwordx4 v130, s[4:5]
	s_mov_b32 m0, s21
	s_add_u32 s4, s76, 0x80000
	global_load_lds_dwordx4 v132, s[76:77]
	s_mov_b32 m0, s26
	s_addc_u32 s5, s77, 0
	s_add_i32 s27, s21, 0x4000
	global_load_lds_dwordx4 v130, s[76:77]
	s_mov_b32 m0, s27
	s_add_i32 s29, s21, 0x6000
	global_load_lds_dwordx4 v132, s[4:5]
	s_mov_b32 m0, s29
	v_mov_b32_e32 v133, v195
	global_load_lds_dwordx4 v130, s[4:5]
	v_mov_b32_e32 v131, v195
	s_cmp_eq_u32 s36, 1
	v_lshl_add_u64 v[8:9], s[84:85], 0, v[132:133]
	v_lshl_add_u64 v[6:7], s[84:85], 0, v[130:131]
	v_lshl_add_u64 v[2:3], s[76:77], 0, v[132:133]
	s_cselect_b64 s[10:11], -1, 0
	s_cmp_lg_u32 s36, 1
	v_lshl_add_u64 v[4:5], s[76:77], 0, v[130:131]
	s_cbranch_scc1 .LBB0_255
	s_barrier

.LBB0_275:
	s_andn2_b64 vcc, exec, s[4:5]
	s_cbranch_vccnz .LBB0_312
	v_readlane_b32 s0, v254, 31
	v_readlane_b32 s1, v254, 32
	s_andn2_b64 vcc, exec, s[0:1]
	v_readfirstlane_b32 s4, v1
	s_cbranch_vccnz .LBB0_312
	v_lshlrev_b32_e32 v13, 4, v1
	v_add_u32_e32 v2, 0x2000, v13
	v_ashrrev_i32_e32 v3, 31, v2
	v_lshrrev_b32_e32 v3, 22, v3
	v_add_u32_e32 v3, v2, v3
	v_ashrrev_i32_e32 v10, 10, v3
	v_mul_i32_i24_e32 v4, 0x400, v10
	v_sub_u32_e32 v2, v2, v4
	v_lshrrev_b32_e32 v4, 4, v2
	v_bitop3_b32 v2, v4, v2, 32 bitop3:0x6c
	v_ashrrev_i32_e32 v4, 31, v2
	v_lshrrev_b32_e32 v4, 26, v4
	v_add_u32_e32 v4, v2, v4
	v_ashrrev_i32_e32 v11, 6, v4
	v_and_b32_e32 v4, 0xc0, v4
	v_sub_u32_e32 v2, v2, v4
	v_lshlrev_b32_e32 v3, 5, v10
	v_ashrrev_i16_sdwa v2, v233, sext(v2) dst_sel:DWORD dst_unused:UNUSED_PAD src0_sel:DWORD src1_sel:BYTE_0
	v_and_b32_e32 v3, 32, v3
	v_bfe_i32 v12, v2, 0, 16
	v_add_u32_e32 v2, v3, v12
	v_lshlrev_b32_e32 v3, 3, v10
	v_and_b32_e32 v3, 0xffff0, v3
	v_add_lshl_u32 v3, v11, v3, 12
	v_lshl_add_u32 v162, v2, 1, v3
	v_bfe_i32 v3, v1, 27, 1
	v_lshrrev_b32_e32 v3, 22, v3
	v_add_u32_e32 v3, v13, v3
	v_and_b32_e32 v3, 0xfffffc00, v3
	v_sub_u32_e32 v3, v13, v3
	v_lshrrev_b32_e32 v4, 4, v3
	v_bitop3_b32 v3, v4, v3, 32 bitop3:0x6c
	v_readlane_b32 s1, v254, 27
	v_ashrrev_i32_e32 v4, 31, v3
	s_mul_hi_u32 s0, s1, 0x1600000
	s_mul_i32 s1, s1, 0x1600000
	v_lshrrev_b32_e32 v4, 26, v4
	s_add_u32 s1, s6, s1
	v_ashrrev_i32_e32 v2, 31, v1
	v_add_u32_e32 v4, v3, v4
	s_addc_u32 s0, s7, s0
	v_lshrrev_b32_e32 v2, 26, v2
	v_ashrrev_i32_e32 v15, 6, v4
	v_and_b32_e32 v4, 0xc0, v4
	s_add_u32 s29, s1, 0x2c00000
	v_add_u32_e32 v2, v1, v2
	v_sub_u32_e32 v3, v3, v4
	s_addc_u32 s31, s0, 0
	s_ashr_i32 s10, s4, 6
	v_ashrrev_i32_e32 v14, 6, v2
	v_ashrrev_i16_sdwa v3, v233, sext(v3) dst_sel:DWORD dst_unused:UNUSED_PAD src0_sel:DWORD src1_sel:BYTE_0
	s_ashr_i32 s98, s4, 8
	s_cbranch_scc0 .Lsprio_skip_ino
	s_setprio 1
.Lsprio_skip_ino:
	s_ashr_i32 s5, s4, 8
	s_lshl_b32 s54, s10, 10
	v_lshlrev_b32_e32 v2, 5, v14
	v_bfe_i32 v16, v3, 0, 16
	v_lshlrev_b32_e32 v3, 3, v14
	v_readlane_b32 s0, v255, 6
	v_and_b32_e32 v2, 32, v2
	v_and_b32_e32 v3, 0xffff0, v3
	v_readlane_b32 s1, v255, 7
	s_add_u32 s70, s29, s0
	v_add_u32_e32 v2, v2, v16
	v_add_lshl_u32 v3, v15, v3, 12
	s_addc_u32 s71, s31, s1
	s_add_i32 s67, s54, 0
	v_lshl_add_u32 v164, v2, 1, v3
	s_add_i32 m0, s67, 0x10000
	v_readlane_b32 s0, v255, 4
	global_load_lds_dwordx4 v164, s[70:71]
	s_add_i32 m0, s67, 0x12000
	s_add_u32 s8, s70, 0x80000
	global_load_lds_dwordx4 v162, s[70:71]
	s_addc_u32 s9, s71, 0
	s_add_i32 m0, s67, 0x14000
	v_readlane_b32 s1, v255, 5
	global_load_lds_dwordx4 v164, s[8:9]
	s_add_i32 m0, s67, 0x16000
	s_add_u32 s76, s79, s0
	s_addc_u32 s77, s28, s1
	s_add_i32 s68, s67, 0x2000
	global_load_lds_dwordx4 v162, s[8:9]
	s_mov_b32 m0, s67
	s_add_u32 s12, s76, 0x80000
	global_load_lds_dwordx4 v164, s[76:77]
	s_mov_b32 m0, s68
	s_addc_u32 s13, s77, 0
	s_add_i32 s8, s67, 0x4000
	global_load_lds_dwordx4 v162, s[76:77]
	s_mov_b32 m0, s8
	s_add_i32 s9, s67, 0x6000
	global_load_lds_dwordx4 v164, s[12:13]
	s_mov_b32 m0, s9
	v_mov_b32_e32 v165, v195
	global_load_lds_dwordx4 v162, s[12:13]
	v_mov_b32_e32 v163, v195
	s_cmp_eq_u32 s5, 1
	v_lshl_add_u64 v[8:9], s[70:71], 0, v[164:165]
	v_lshl_add_u64 v[6:7], s[70:71], 0, v[162:163]
	v_lshl_add_u64 v[2:3], s[76:77], 0, v[164:165]
	s_cselect_b64 s[84:85], -1, 0
	s_cmp_lg_u32 s5, 1
	v_lshl_add_u64 v[4:5], s[76:77], 0, v[162:163]
	s_cbranch_scc1 .LBB0_279
	s_barrier

.LBB0_495:
	v_readlane_b32 s4, v254, 1
	v_readlane_b32 s5, v254, 2
	s_cmp_le_i32 s4, s8
	s_cselect_b64 s[0:1], -1, 0
	s_cmp_lt_i32 s8, s5
	s_cselect_b64 s[4:5], -1, 0
	s_and_b64 s[0:1], s[0:1], s[4:5]
	s_andn2_b64 vcc, exec, s[0:1]
	v_readlane_b32 s0, v254, 18
	v_readlane_b32 s1, v254, 19
	v_readlane_b32 s6, v254, 3
	v_readlane_b32 s7, v254, 4
	v_cndmask_b32_e64 v1, 0, 1, s[0:1]
	v_cmp_ne_u32_e64 s[4:5], 1, v1
	s_cbranch_vccnz .LBB0_534
	v_mov_b32_e32 v1, v0
	s_mov_b32 s6, 19
	s_and_b64 vcc, exec, s[4:5]
	v_readfirstlane_b32 s22, v1
	s_cbranch_vccnz .LBB0_534
	v_lshlrev_b32_e32 v10, 4, v1
	v_add_u32_e32 v2, 0x2000, v10
	v_ashrrev_i32_e32 v3, 31, v2
	v_lshrrev_b32_e32 v3, 22, v3
	v_add_u32_e32 v3, v2, v3
	v_ashrrev_i32_e32 v11, 10, v3
	v_mul_i32_i24_e32 v3, 0x400, v11
	v_sub_u32_e32 v2, v2, v3
	s_ashr_i32 s7, s6, 31
	v_lshrrev_b32_e32 v3, 4, v2
	s_lshl_b64 s[0:1], s[6:7], 3
	v_readlane_b32 s6, v254, 7
	v_bitop3_b32 v2, v3, v2, 32 bitop3:0x6c
	v_readlane_b32 s7, v254, 8
	s_add_u32 s0, s6, s0
	v_ashrrev_i32_e32 v3, 31, v2
	s_addc_u32 s1, s7, s1
	v_lshrrev_b32_e32 v3, 26, v3
	s_load_dwordx2 s[6:7], s[0:1], 0x0
	v_add_u32_e32 v3, v2, v3
	v_ashrrev_i32_e32 v12, 6, v3
	v_and_b32_e32 v3, 0xc0, v3
	v_sub_u32_e32 v2, v2, v3
	v_ashrrev_i16_sdwa v2, v233, sext(v2) dst_sel:DWORD dst_unused:UNUSED_PAD src0_sel:DWORD src1_sel:BYTE_0
	v_bfe_i32 v14, v2, 0, 16
	v_bfe_i32 v2, v1, 27, 1
	s_waitcnt lgkmcnt(0)
	s_add_u32 s20, s6, 0x3b000000
	v_readlane_b32 s0, v254, 27
	v_lshrrev_b32_e32 v2, 22, v2
	s_addc_u32 s21, s7, 0
	s_lshl_b32 s8, s0, 23
	v_readlane_b32 s0, v254, 16
	v_lshlrev_b32_e32 v4, 3, v11
	v_add_u32_e32 v2, v10, v2
	v_readlane_b32 s1, v254, 17
	v_and_b32_e32 v4, 0xffff0, v4
	v_lshlrev_b32_e32 v5, 5, v11
	v_and_b32_e32 v2, 0xfffffc00, v2
	s_and_b64 s[0:1], s[0:1], exec
	v_add_u32_e32 v4, v12, v4
	v_and_b32_e32 v13, 32, v5
	v_sub_u32_e32 v2, v10, v2
	s_mov_b32 s0, 0x5800000
	v_lshl_or_b32 v4, v4, 11, v13
	v_lshrrev_b32_e32 v3, 4, v2
	s_cselect_b32 s0, s0, 0x9800000
	v_add_lshl_u32 v204, v4, v14, 1
	v_bitop3_b32 v2, v3, v2, 32 bitop3:0x6c
	v_ashrrev_i32_e32 v4, 31, v1
	s_add_u32 s0, s6, s0
	v_ashrrev_i32_e32 v3, 31, v2
	v_lshrrev_b32_e32 v4, 26, v4
	s_addc_u32 s1, s7, 0
	v_lshrrev_b32_e32 v3, 26, v3
	v_add_u32_e32 v4, v1, v4
	s_add_u32 s26, s0, s8
	v_add_u32_e32 v3, v2, v3
	v_ashrrev_i32_e32 v16, 6, v4
	s_addc_u32 s27, s1, 0
	s_ashr_i32 s23, s22, 6
	v_ashrrev_i32_e32 v15, 6, v3
	v_lshlrev_b32_e32 v4, 3, v16
	v_and_b32_e32 v3, 0xc0, v3
	s_ashr_i32 s98, s22, 8
	s_cbranch_scc0 .Lsprio_skip_out
	s_setprio 1
.Lsprio_skip_out:
	s_ashr_i32 s40, s22, 8
	s_lshl_b32 s28, s23, 10
	v_and_b32_e32 v4, 0xffff0, v4
	v_lshlrev_b32_e32 v5, 5, v16
	v_sub_u32_e32 v2, v2, v3
	v_readlane_b32 s0, v255, 10
	v_add_u32_e32 v4, v15, v4
	v_and_b32_e32 v17, 32, v5
	v_ashrrev_i16_sdwa v2, v233, sext(v2) dst_sel:DWORD dst_unused:UNUSED_PAD src0_sel:DWORD src1_sel:BYTE_0
	v_readlane_b32 s1, v255, 11
	s_add_u32 s90, s26, s0
	v_lshl_or_b32 v4, v4, 11, v17
	v_bfe_i32 v18, v2, 0, 16
	s_addc_u32 s91, s27, s1
	s_add_i32 s29, s28, 0
	v_add_lshl_u32 v194, v4, v18, 1
	s_add_i32 m0, s29, 0x10000
	v_mov_b32_e32 v205, v195
	global_load_lds_dwordx4 v194, s[90:91]
	s_add_i32 m0, s29, 0x12000
	s_add_u32 s0, s90, 0x80000
	global_load_lds_dwordx4 v204, s[90:91]
	s_addc_u32 s1, s91, 0
	s_add_i32 m0, s29, 0x14000
	v_lshl_add_u64 v[8:9], s[90:91], 0, v[194:195]
	global_load_lds_dwordx4 v194, s[0:1]
	s_add_i32 m0, s29, 0x16000
	v_lshl_add_u64 v[6:7], s[90:91], 0, v[204:205]
	global_load_lds_dwordx4 v204, s[0:1]
	v_readlane_b32 s0, v255, 8
	v_readlane_b32 s1, v255, 9
	s_add_u32 s76, s20, s0
	s_addc_u32 s77, s21, s1
	s_add_i32 s31, s29, 0x2000
	s_mov_b32 m0, s29
	s_add_u32 s0, s76, 0x80000
	global_load_lds_dwordx4 v194, s[76:77]
	s_mov_b32 m0, s31
	s_addc_u32 s1, s77, 0
	s_add_i32 s33, s29, 0x4000
	global_load_lds_dwordx4 v204, s[76:77]
	s_mov_b32 m0, s33
	s_add_i32 s43, s29, 0x6000
	global_load_lds_dwordx4 v194, s[0:1]
	s_mov_b32 m0, s43
	s_cmp_eq_u32 s40, 1
	global_load_lds_dwordx4 v204, s[0:1]
	v_lshl_add_u64 v[2:3], s[76:77], 0, v[194:195]
	s_cselect_b64 s[8:9], -1, 0
	s_cmp_lg_u32 s40, 1
	v_lshl_add_u64 v[4:5], s[76:77], 0, v[204:205]
	s_cbranch_scc1 .LBB0_499
	s_barrier

.LBB0_571:
	s_add_i32 s6, s42, 9
	v_readlane_b32 s8, v254, 1
	v_readlane_b32 s9, v254, 2
	s_cmp_le_i32 s8, s6
	s_cselect_b64 s[0:1], -1, 0
	s_cmp_lt_i32 s6, s9
	s_cselect_b64 s[6:7], -1, 0
	s_and_b64 s[0:1], s[0:1], s[6:7]
	s_andn2_b64 vcc, exec, s[0:1]
	v_readlane_b32 s10, v254, 3
	v_readlane_b32 s11, v254, 4
	s_cbranch_vccnz .LBB0_590
	v_readlane_b32 s0, v254, 49
	v_mov_b32_e32 v1, v0
	v_readlane_b32 s1, v254, 50
	s_mov_b32 s6, 19
	s_andn2_b64 vcc, exec, s[0:1]
	v_readfirstlane_b32 s22, v1
	s_cbranch_vccnz .LBB0_590
	v_lshlrev_b32_e32 v13, 4, v1
	v_add_u32_e32 v2, 0x2000, v13
	v_ashrrev_i32_e32 v3, 31, v2
	v_lshrrev_b32_e32 v3, 22, v3
	v_add_u32_e32 v3, v2, v3
	v_ashrrev_i32_e32 v10, 10, v3
	v_mul_i32_i24_e32 v4, 0x400, v10
	v_sub_u32_e32 v2, v2, v4
	v_lshrrev_b32_e32 v4, 4, v2
	v_bitop3_b32 v2, v4, v2, 32 bitop3:0x6c
	v_ashrrev_i32_e32 v4, 31, v2
	v_lshrrev_b32_e32 v4, 26, v4
	v_add_u32_e32 v4, v2, v4
	v_ashrrev_i32_e32 v11, 6, v4
	v_and_b32_e32 v4, 0xc0, v4
	v_sub_u32_e32 v2, v2, v4
	v_lshlrev_b32_e32 v3, 5, v10
	v_ashrrev_i16_sdwa v2, v233, sext(v2) dst_sel:DWORD dst_unused:UNUSED_PAD src0_sel:DWORD src1_sel:BYTE_0
	v_and_b32_e32 v3, 32, v3
	v_bfe_i32 v12, v2, 0, 16
	v_add_u32_e32 v2, v3, v12
	v_lshlrev_b32_e32 v3, 3, v10
	s_ashr_i32 s7, s6, 31
	v_and_b32_e32 v3, 0xffff0, v3
	s_lshl_b64 s[0:1], s[6:7], 3
	v_readlane_b32 s6, v254, 7
	v_add_lshl_u32 v3, v11, v3, 12
	v_readlane_b32 s7, v254, 8
	s_add_u32 s0, s6, s0
	v_lshl_add_u32 v130, v2, 1, v3
	v_bfe_i32 v3, v1, 27, 1
	s_addc_u32 s1, s7, s1
	v_lshrrev_b32_e32 v3, 22, v3
	s_load_dwordx2 s[6:7], s[0:1], 0x0
	v_add_u32_e32 v3, v13, v3
	v_and_b32_e32 v3, 0xfffffc00, v3
	v_sub_u32_e32 v3, v13, v3
	v_lshrrev_b32_e32 v4, 4, v3
	v_bitop3_b32 v3, v4, v3, 32 bitop3:0x6c
	s_waitcnt lgkmcnt(0)
	s_add_u32 s20, s6, 0x1b000000
	v_ashrrev_i32_e32 v4, 31, v3
	s_mul_i32 s1, s75, 0x2c00000
	s_addc_u32 s21, s7, 0
	v_lshrrev_b32_e32 v4, 26, v4
	s_mul_hi_u32 s0, s75, 0x2c00000
	s_add_u32 s1, s6, s1
	v_ashrrev_i32_e32 v2, 31, v1
	v_add_u32_e32 v4, v3, v4
	s_addc_u32 s0, s7, s0
	v_lshrrev_b32_e32 v2, 26, v2
	v_ashrrev_i32_e32 v15, 6, v4
	v_and_b32_e32 v4, 0xc0, v4
	s_add_u32 s26, s1, 0xa800000
	v_add_u32_e32 v2, v1, v2
	v_sub_u32_e32 v3, v3, v4
	s_addc_u32 s27, s0, 0
	s_ashr_i32 s12, s22, 6
	v_ashrrev_i32_e32 v14, 6, v2
	v_ashrrev_i16_sdwa v3, v233, sext(v3) dst_sel:DWORD dst_unused:UNUSED_PAD src0_sel:DWORD src1_sel:BYTE_0
	s_ashr_i32 s98, s22, 8
	s_cbranch_scc0 .Lsprio_skip_gu
	s_setprio 1
.Lsprio_skip_gu:
	s_ashr_i32 s13, s22, 8
	s_lshl_b32 s28, s12, 10
	v_lshlrev_b32_e32 v2, 5, v14
	v_bfe_i32 v16, v3, 0, 16
	v_lshlrev_b32_e32 v3, 3, v14
	v_readlane_b32 s0, v255, 0
	v_and_b32_e32 v2, 32, v2
	v_and_b32_e32 v3, 0xffff0, v3
	v_readlane_b32 s1, v255, 1
	s_add_u32 s64, s26, s0
	v_add_u32_e32 v2, v2, v16
	v_add_lshl_u32 v3, v15, v3, 12
	s_addc_u32 s65, s27, s1
	s_add_i32 s29, s28, 0
	v_lshl_add_u32 v194, v2, 1, v3
	s_add_i32 m0, s29, 0x10000
	v_mov_b32_e32 v131, v195
	global_load_lds_dwordx4 v194, s[64:65]
	s_add_i32 m0, s29, 0x12000
	s_add_u32 s0, s64, 0x80000
	global_load_lds_dwordx4 v130, s[64:65]
	s_addc_u32 s1, s65, 0
	s_add_i32 m0, s29, 0x14000
	v_lshl_add_u64 v[8:9], s[64:65], 0, v[194:195]
	global_load_lds_dwordx4 v194, s[0:1]
	s_add_i32 m0, s29, 0x16000
	v_lshl_add_u64 v[6:7], s[64:65], 0, v[130:131]
	global_load_lds_dwordx4 v130, s[0:1]
	v_readlane_b32 s0, v254, 62
	v_readlane_b32 s1, v254, 63
	s_add_u32 s62, s20, s0
	s_addc_u32 s63, s21, s1
	s_add_i32 s31, s29, 0x2000
	s_mov_b32 m0, s29
	s_add_u32 s0, s62, 0x80000
	global_load_lds_dwordx4 v194, s[62:63]
	s_mov_b32 m0, s31
	s_addc_u32 s1, s63, 0
	s_add_i32 s33, s29, 0x4000
	global_load_lds_dwordx4 v130, s[62:63]
	s_mov_b32 m0, s33
	s_add_i32 s40, s29, 0x6000
	global_load_lds_dwordx4 v194, s[0:1]
	s_mov_b32 m0, s40
	s_cmp_eq_u32 s13, 1
	global_load_lds_dwordx4 v130, s[0:1]
	v_lshl_add_u64 v[2:3], s[62:63], 0, v[194:195]
	s_cselect_b64 s[8:9], -1, 0
	s_cmp_lg_u32 s13, 1
	v_lshl_add_u64 v[4:5], s[62:63], 0, v[130:131]
	s_cbranch_scc1 .LBB0_575
	s_barrier

.LBB0_627:
	v_readlane_b32 s8, v254, 1
	s_cmp_gt_i32 s8, s20
	s_cselect_b64 s[0:1], -1, 0
	s_xor_b64 s[6:7], s[6:7], -1
	s_or_b64 s[0:1], s[0:1], s[6:7]
	s_and_b64 vcc, exec, s[0:1]
	v_readlane_b32 s9, v254, 2
	v_readlane_b32 s10, v254, 3
	v_readlane_b32 s11, v254, 4
	s_cbranch_vccnz .LBB0_702
	v_mov_b32_e32 v1, v0
	s_mov_b32 s6, 19
	s_and_b64 vcc, exec, s[4:5]
	v_readfirstlane_b32 s22, v1
	s_cbranch_vccnz .LBB0_702
	v_lshlrev_b32_e32 v2, 4, v1
	v_add_u32_e32 v3, 0x2000, v2
	v_ashrrev_i32_e32 v4, 31, v3
	v_lshrrev_b32_e32 v4, 22, v4
	v_add_u32_e32 v4, v3, v4
	v_ashrrev_i32_e32 v10, 10, v4
	v_mul_i32_i24_e32 v4, 0x400, v10
	v_sub_u32_e32 v3, v3, v4
	v_lshrrev_b32_e32 v4, 4, v3
	v_bitop3_b32 v3, v4, v3, 32 bitop3:0x6c
	v_ashrrev_i32_e32 v4, 31, v3
	s_ashr_i32 s7, s6, 31
	v_lshrrev_b32_e32 v4, 26, v4
	s_lshl_b64 s[0:1], s[6:7], 3
	v_readlane_b32 s4, v254, 7
	v_add_u32_e32 v4, v3, v4
	v_readlane_b32 s5, v254, 8
	s_add_u32 s0, s4, s0
	v_ashrrev_i32_e32 v11, 6, v4
	v_and_b32_e32 v4, 0xc0, v4
	s_addc_u32 s1, s5, s1
	v_sub_u32_e32 v3, v3, v4
	s_load_dwordx2 s[4:5], s[0:1], 0x0
	v_ashrrev_i16_sdwa v3, v233, sext(v3) dst_sel:DWORD dst_unused:UNUSED_PAD src0_sel:DWORD src1_sel:BYTE_0
	v_bfe_i32 v13, v3, 0, 16
	v_bfe_i32 v3, v1, 27, 1
	v_lshrrev_b32_e32 v3, 22, v3
	v_add_u32_e32 v3, v2, v3
	v_and_b32_e32 v3, 0xfffffc00, v3
	s_waitcnt lgkmcnt(0)
	s_add_u32 s20, s4, 0x23000000
	v_sub_u32_e32 v2, v2, v3
	s_mul_i32 s1, s75, 0x1600000
	s_addc_u32 s21, s5, 0
	v_lshrrev_b32_e32 v3, 4, v2
	v_ashrrev_i32_e32 v4, 31, v1
	s_mul_hi_u32 s0, s75, 0x1600000
	s_add_u32 s1, s4, s1
	v_bitop3_b32 v2, v3, v2, 32 bitop3:0x6c
	v_lshrrev_b32_e32 v4, 26, v4
	s_addc_u32 s0, s5, s0
	v_lshlrev_b32_e32 v5, 3, v10
	v_ashrrev_i32_e32 v3, 31, v2
	v_add_u32_e32 v4, v1, v4
	s_add_u32 s26, s1, 0x15800000
	v_and_b32_e32 v5, 0x7ffff0, v5
	v_lshrrev_b32_e32 v3, 26, v3
	v_ashrrev_i32_e32 v15, 6, v4
	s_addc_u32 s27, s0, 0
	v_add_u32_e32 v5, v11, v5
	s_movk_i32 s0, 0x1600
	v_lshlrev_b32_e32 v6, 5, v10
	v_add_u32_e32 v3, v2, v3
	v_lshlrev_b32_e32 v4, 3, v15
	v_mul_lo_u32 v5, v5, s0
	v_and_b32_e32 v12, 32, v6
	v_ashrrev_i32_e32 v14, 6, v3
	v_and_b32_e32 v4, 0x7ffff0, v4
	s_ashr_i32 s6, s22, 6
	v_or_b32_e32 v5, v5, v12
	v_add_u32_e32 v4, v14, v4
	v_and_b32_e32 v3, 0xc0, v3
	v_readlane_b32 s1, v254, 22
	s_ashr_i32 s98, s22, 8
	s_cbranch_scc0 .Lsprio_skip_down
	s_setprio 1
.Lsprio_skip_down:
	s_ashr_i32 s7, s22, 8
	s_lshl_b32 s28, s6, 10
	v_add_lshl_u32 v190, v5, v13, 1
	v_mul_lo_u32 v4, v4, s0
	v_lshlrev_b32_e32 v5, 5, v15
	v_sub_u32_e32 v2, v2, v3
	s_mul_i32 s0, s1, 0x2c0000
	v_and_b32_e32 v16, 32, v5
	v_ashrrev_i16_sdwa v2, v233, sext(v2) dst_sel:DWORD dst_unused:UNUSED_PAD src0_sel:DWORD src1_sel:BYTE_0
	s_add_u32 s64, s26, s0
	s_mul_hi_i32 s0, s1, 0x2c0000
	v_or_b32_e32 v4, v4, v16
	v_bfe_i32 v17, v2, 0, 16
	s_addc_u32 s65, s27, s0
	s_add_i32 s29, s28, 0
	v_add_lshl_u32 v192, v4, v17, 1
	s_add_i32 m0, s29, 0x10000
	v_mov_b32_e32 v193, v195
	global_load_lds_dwordx4 v192, s[64:65]
	s_add_i32 m0, s29, 0x12000
	s_add_u32 s0, s64, 0x160000
	global_load_lds_dwordx4 v190, s[64:65]
	s_addc_u32 s1, s65, 0
	s_add_i32 m0, s29, 0x14000
	v_mov_b32_e32 v191, v195
	global_load_lds_dwordx4 v192, s[0:1]
	s_add_i32 m0, s29, 0x16000
	v_lshl_add_u64 v[8:9], s[64:65], 0, v[192:193]
	global_load_lds_dwordx4 v190, s[0:1]
	v_readlane_b32 s0, v254, 20
	s_mov_b32 s10, s0
	s_mul_i32 s0, s0, 0x2c0000
	s_add_u32 s8, s20, s0
	s_mul_hi_i32 s0, s10, 0x2c0000
	s_addc_u32 s9, s21, s0
	s_add_i32 s31, s29, 0x2000
	v_readlane_b32 s1, v254, 21
	s_mov_b32 m0, s29
	s_add_u32 s0, s8, 0x160000
	global_load_lds_dwordx4 v192, s[8:9]
	s_mov_b32 m0, s31
	s_addc_u32 s1, s9, 0
	s_add_i32 s33, s29, 0x4000
	global_load_lds_dwordx4 v190, s[8:9]
	s_mov_b32 m0, s33
	s_add_i32 s43, s29, 0x6000
	global_load_lds_dwordx4 v192, s[0:1]
	s_mov_b32 m0, s43
	s_cmp_eq_u32 s7, 1
	global_load_lds_dwordx4 v190, s[0:1]
	v_lshl_add_u64 v[6:7], s[64:65], 0, v[190:191]
	v_lshl_add_u64 v[2:3], s[8:9], 0, v[192:193]
	s_cselect_b64 s[10:11], -1, 0
	s_cmp_lg_u32 s7, 1
	v_lshl_add_u64 v[4:5], s[8:9], 0, v[190:191]
	s_cbranch_scc1 .LBB0_631
	s_barrier
